# grid barrier: waiting blocks issue their L1 invalidate before polling for the release instead of after it
# baseline (speedup 1.0000x reference)
; __device__ __forceinline__ unsigned xb_ld(unsigned* p)              { return __hip_atomic_load(p, __ATOMIC_RELAXED, __HIP_MEMORY_SCOPE_AGENT); }
; __device__ __forceinline__ unsigned xb_add(unsigned* p, unsigned v) { return __hip_atomic_fetch_add(p, v, __ATOMIC_RELAXED, __HIP_MEMORY_SCOPE_AGENT); }
; #define XB_SPIN(cond, bar) do { unsigned _sp = 0; while (cond) { __builtin_amdgcn_s_sleep(1); \
;     if ((++_sp & 255u) == 0u) { if (xb_ld(&(bar)[XB_TMO])) break; if (_sp > XB_SPIN_CAP) { atomicAdd(&(bar)[XB_TMO], 1u); break; } } } } while (0)
; __device__ __forceinline__ void xcd_barrier(const XcdBarrier& b) {
;     ...
;         const unsigned old = xb_add(&bar[XB_XSUB(b.x)], 1u);
;         const unsigned gen = old / nloc;
;         if (old + 1u == (gen + 1u) * nloc) {
;             __builtin_amdgcn_fence(__ATOMIC_RELEASE, "agent");
;             asm volatile("s_waitcnt vmcnt(0)" ::: "memory");
;             const unsigned og = xb_add(&bar[XB_TOP], 1u);
;             const unsigned tg = og / nx;
;             if (og + 1u == (tg + 1u) * nx) xb_add(&bar[XB_TOPGEN], 1u);
;             else XB_SPIN(xb_ld(&bar[XB_TOPGEN]) == tg, bar);
;             __builtin_amdgcn_fence(__ATOMIC_ACQUIRE, "agent");
;             xb_add(&bar[XB_XGEN(b.x)], 1u);
;             asm volatile("s_waitcnt vmcnt(0)" ::: "memory");
;         } else {
;             XB_SPIN(xb_ld(&bar[XB_XGEN(b.x)]) == gen, bar);
;             __builtin_amdgcn_fence(__ATOMIC_ACQUIRE, "agent");
;             asm volatile("s_waitcnt vmcnt(0)" ::: "memory");
.LBB0_148:
	s_or_b64 exec, exec, s[14:15]
	v_cvt_f32_u32_e32 v5, v3
	s_waitcnt vmcnt(0)
	v_readfirstlane_b32 s14, v4
	v_sub_u32_e32 v4, 0, v3
	v_rcp_iflag_f32_e32 v5, v5
	v_add_u32_e32 v6, s14, v0
	v_mul_f32_e32 v5, 0x4f7ffffe, v5
	v_cvt_u32_f32_e32 v5, v5
	v_mul_lo_u32 v0, v4, v5
	v_mul_hi_u32 v0, v5, v0
	v_add_u32_e32 v0, v5, v0
	v_mul_hi_u32 v0, v6, v0
	v_mul_lo_u32 v4, v0, v3
	v_sub_u32_e32 v4, v6, v4
	v_add_u32_e32 v5, 1, v0
	v_cmp_ge_u32_e32 vcc, v4, v3
	s_nop 1
	v_cndmask_b32_e32 v0, v0, v5, vcc
	v_sub_u32_e32 v5, v4, v3
	v_cndmask_b32_e32 v4, v4, v5, vcc
	v_add_u32_e32 v5, 1, v0
	v_cmp_ge_u32_e32 vcc, v4, v3
	v_add_u32_e32 v4, 1, v6
	s_nop 0
	v_cndmask_b32_e32 v0, v0, v5, vcc
	v_mul_lo_u32 v5, v3, v0
	v_add_u32_e32 v3, v5, v3
	v_cmp_ne_u32_e32 vcc, v4, v3
	s_and_saveexec_b64 s[14:15], vcc
	s_xor_b64 s[14:15], exec, s[14:15]
	s_cbranch_execz .LBB0_162
	buffer_inv sc1
	v_readlane_b32 s16, v252, 57
	v_readlane_b32 s17, v252, 58
	s_waitcnt lgkmcnt(0)
	s_nop 3
	global_load_dword v2, v1, s[16:17] sc1
	s_waitcnt vmcnt(0)
	v_cmp_eq_u32_e32 vcc, v2, v0
	s_and_saveexec_b64 s[16:17], vcc
	s_cbranch_execz .LBB0_161
	s_mov_b32 s40, 1
	s_mov_b64 s[18:19], 0
	s_branch .LBB0_152

; __device__ __forceinline__ unsigned xb_ld(unsigned* p)              { return __hip_atomic_load(p, __ATOMIC_RELAXED, __HIP_MEMORY_SCOPE_AGENT); }
; #define XB_SPIN(cond, bar) do { unsigned _sp = 0; while (cond) { __builtin_amdgcn_s_sleep(1); \
;     if ((++_sp & 255u) == 0u) { if (xb_ld(&(bar)[XB_TMO])) break; if (_sp > XB_SPIN_CAP) { atomicAdd(&(bar)[XB_TMO], 1u); break; } } } } while (0)
; __device__ __forceinline__ void xcd_barrier(const XcdBarrier& b) {
;     ...
;             XB_SPIN(xb_ld(&bar[XB_XGEN(b.x)]) == gen, bar);
;             __builtin_amdgcn_fence(__ATOMIC_ACQUIRE, "agent");
;             asm volatile("s_waitcnt vmcnt(0)" ::: "memory");
.LBB0_161:
	s_or_b64 exec, exec, s[16:17]
	s_waitcnt vmcnt(0)
	s_waitcnt vmcnt(0)

; __device__ __forceinline__ unsigned xb_ld(unsigned* p)              { return __hip_atomic_load(p, __ATOMIC_RELAXED, __HIP_MEMORY_SCOPE_AGENT); }
; __device__ __forceinline__ unsigned xb_add(unsigned* p, unsigned v) { return __hip_atomic_fetch_add(p, v, __ATOMIC_RELAXED, __HIP_MEMORY_SCOPE_AGENT); }
; #define XB_SPIN(cond, bar) do { unsigned _sp = 0; while (cond) { __builtin_amdgcn_s_sleep(1); \
;     if ((++_sp & 255u) == 0u) { if (xb_ld(&(bar)[XB_TMO])) break; if (_sp > XB_SPIN_CAP) { atomicAdd(&(bar)[XB_TMO], 1u); break; } } } } while (0)
; __device__ __forceinline__ void xcd_barrier(const XcdBarrier& b) {
;     ...
;         const unsigned old = xb_add(&bar[XB_XSUB(b.x)], 1u);
;         const unsigned gen = old / nloc;
;         if (old + 1u == (gen + 1u) * nloc) {
;             __builtin_amdgcn_fence(__ATOMIC_RELEASE, "agent");
;             asm volatile("s_waitcnt vmcnt(0)" ::: "memory");
;             const unsigned og = xb_add(&bar[XB_TOP], 1u);
;             const unsigned tg = og / nx;
;             if (og + 1u == (tg + 1u) * nx) xb_add(&bar[XB_TOPGEN], 1u);
;             else XB_SPIN(xb_ld(&bar[XB_TOPGEN]) == tg, bar);
;             __builtin_amdgcn_fence(__ATOMIC_ACQUIRE, "agent");
;             xb_add(&bar[XB_XGEN(b.x)], 1u);
;             asm volatile("s_waitcnt vmcnt(0)" ::: "memory");
;         } else {
;             XB_SPIN(xb_ld(&bar[XB_XGEN(b.x)]) == gen, bar);
;             __builtin_amdgcn_fence(__ATOMIC_ACQUIRE, "agent");
;             asm volatile("s_waitcnt vmcnt(0)" ::: "memory");
.LBB0_444:
	s_or_b64 exec, exec, s[4:5]
	v_cvt_f32_u32_e32 v5, v3
	s_waitcnt vmcnt(0)
	v_readfirstlane_b32 s4, v4
	v_sub_u32_e32 v4, 0, v3
	v_rcp_iflag_f32_e32 v5, v5
	v_add_u32_e32 v6, s4, v0
	v_mul_f32_e32 v5, 0x4f7ffffe, v5
	v_cvt_u32_f32_e32 v5, v5
	v_mul_lo_u32 v0, v4, v5
	v_mul_hi_u32 v0, v5, v0
	v_add_u32_e32 v0, v5, v0
	v_mul_hi_u32 v0, v6, v0
	v_mul_lo_u32 v4, v0, v3
	v_sub_u32_e32 v4, v6, v4
	v_add_u32_e32 v5, 1, v0
	v_cmp_ge_u32_e32 vcc, v4, v3
	s_nop 1
	v_cndmask_b32_e32 v0, v0, v5, vcc
	v_sub_u32_e32 v5, v4, v3
	v_cndmask_b32_e32 v4, v4, v5, vcc
	v_add_u32_e32 v5, 1, v0
	v_cmp_ge_u32_e32 vcc, v4, v3
	v_add_u32_e32 v4, 1, v6
	s_nop 0
	v_cndmask_b32_e32 v0, v0, v5, vcc
	v_mul_lo_u32 v5, v3, v0
	v_add_u32_e32 v3, v5, v3
	v_cmp_ne_u32_e32 vcc, v4, v3
	s_and_saveexec_b64 s[4:5], vcc
	s_xor_b64 s[4:5], exec, s[4:5]
	s_cbranch_execz .LBB0_458
	buffer_inv sc1
	v_readlane_b32 s14, v252, 57
	v_readlane_b32 s15, v252, 58
	s_waitcnt lgkmcnt(0)
	s_nop 3
	global_load_dword v2, v1, s[14:15] sc1
	s_waitcnt vmcnt(0)
	v_cmp_eq_u32_e32 vcc, v2, v0
	s_and_saveexec_b64 s[14:15], vcc
	s_cbranch_execz .LBB0_457
	s_mov_b32 s34, 1
	s_mov_b64 s[16:17], 0
	s_branch .LBB0_448

; __device__ __forceinline__ unsigned xb_ld(unsigned* p)              { return __hip_atomic_load(p, __ATOMIC_RELAXED, __HIP_MEMORY_SCOPE_AGENT); }
; #define XB_SPIN(cond, bar) do { unsigned _sp = 0; while (cond) { __builtin_amdgcn_s_sleep(1); \
;     if ((++_sp & 255u) == 0u) { if (xb_ld(&(bar)[XB_TMO])) break; if (_sp > XB_SPIN_CAP) { atomicAdd(&(bar)[XB_TMO], 1u); break; } } } } while (0)
; __device__ __forceinline__ void xcd_barrier(const XcdBarrier& b) {
;     ...
;             XB_SPIN(xb_ld(&bar[XB_XGEN(b.x)]) == gen, bar);
;             __builtin_amdgcn_fence(__ATOMIC_ACQUIRE, "agent");
;             asm volatile("s_waitcnt vmcnt(0)" ::: "memory");
.LBB0_457:
	s_or_b64 exec, exec, s[14:15]
	s_waitcnt vmcnt(0)
	s_waitcnt vmcnt(0)
